# final RMSNorm: weight vector loaded once before the row loop (was 8 serialized store+load+wait groups per row)
# speedup vs baseline: 1.0107x; 1.0051x over previous
.LBB0_1807:
	s_or_b64 exec, exec, s[2:3]
	s_waitcnt lgkmcnt(0)
	v_mov_b64_e32 v[0:1], s[58:59]
	s_barrier
	flat_load_dwordx2 v[0:1], v[0:1] offset:352 sc0 sc1
	s_waitcnt vmcnt(0)
	v_readfirstlane_b32 s0, v254
	s_ashr_i32 s2, s0, 6
	v_readlane_b32 s5, v255, 6
	s_add_i32 s4, s2, s5
	s_cmpk_lt_i32 s4, 0x2000
	s_waitcnt lgkmcnt(0)
	v_readfirstlane_b32 s1, v1
	v_readfirstlane_b32 s0, v0
	s_cbranch_scc0 .LBB0_1810
	v_mbcnt_lo_u32_b32 v0, -1, 0
	v_mbcnt_hi_u32_b32 v0, -1, v0
	v_and_b32_e32 v1, 64, v0
	v_add_u32_e32 v1, 64, v1
	v_xor_b32_e32 v2, 1, v0
	v_cmp_lt_i32_e32 vcc, v2, v1
	s_load_dwordx2 s[6:7], s[88:89], 0x168
	s_ashr_i32 s3, s5, 31
	v_cndmask_b32_e32 v2, v0, v2, vcc
	v_lshlrev_b32_e32 v16, 2, v2
	v_xor_b32_e32 v2, 2, v0
	v_cmp_lt_i32_e32 vcc, v2, v1
	v_mov_b32_e32 v22, 0x358637bd
	v_mov_b32_e32 v23, 0x260
	v_cndmask_b32_e32 v2, v0, v2, vcc
	v_lshlrev_b32_e32 v17, 2, v2
	v_xor_b32_e32 v2, 4, v0
	v_cmp_lt_i32_e32 vcc, v2, v1
	s_nop 1
	v_cndmask_b32_e32 v2, v0, v2, vcc
	v_lshlrev_b32_e32 v18, 2, v2
	v_xor_b32_e32 v2, 8, v0
	v_cmp_lt_i32_e32 vcc, v2, v1
	s_nop 1
	v_cndmask_b32_e32 v2, v0, v2, vcc
	v_lshlrev_b32_e32 v19, 2, v2
	v_xor_b32_e32 v2, 16, v0
	v_cmp_lt_i32_e32 vcc, v2, v1
	s_nop 1
	v_cndmask_b32_e32 v2, v0, v2, vcc
	v_lshlrev_b32_e32 v20, 2, v2
	v_xor_b32_e32 v2, 32, v0
	v_cmp_lt_i32_e32 vcc, v2, v1
	v_mov_b32_e32 v1, 0
	v_mov_b32_e32 v3, v1
	v_cndmask_b32_e32 v0, v0, v2, vcc
	v_lshlrev_b32_e32 v21, 2, v0
	v_lshlrev_b32_e32 v0, 4, v254
	v_and_b32_e32 v0, 0x3f0, v0
	v_or_b32_e32 v2, 0x1000, v0
	v_lshl_add_u64 v[6:7], s[0:1], 0, v[2:3]
	v_or_b32_e32 v2, 0x1400, v0
	v_lshl_add_u64 v[4:5], s[0:1], 0, v[0:1]
	v_lshl_add_u64 v[8:9], s[0:1], 0, v[2:3]
	v_or_b32_e32 v2, 0x1800, v0
	v_or_b32_e32 v0, 0x1c00, v0
	v_lshl_add_u64 v[10:11], s[0:1], 0, v[2:3]
	v_lshl_add_u64 v[12:13], s[0:1], 0, v[0:1]
	s_ashr_i32 s1, s2, 31
	s_add_u32 s0, s2, s5
	s_addc_u32 s1, s1, s3
	s_lshl_b64 s[0:1], s[0:1], 13
	v_and_b32_e32 v0, 63, v254
	s_waitcnt lgkmcnt(0)
	s_add_u32 s0, s6, s0
	v_lshlrev_b32_e32 v0, 4, v0
	s_addc_u32 s1, s7, s1
	v_lshl_add_u64 v[0:1], s[0:1], 0, v[0:1]
	s_mov_b64 s[0:1], 0x1c00
	s_ashr_i32 s23, s22, 31
	v_lshl_add_u64 v[14:15], v[0:1], 0, s[0:1]
	s_lshl_b64 s[2:3], s[22:23], 13
	s_mov_b32 s5, 0xf800000
	flat_load_dwordx4 v[150:153], v[4:5]
	flat_load_dwordx4 v[154:157], v[4:5] offset:1024
	flat_load_dwordx4 v[158:161], v[4:5] offset:2048
	flat_load_dwordx4 v[162:165], v[4:5] offset:3072
	flat_load_dwordx4 v[166:169], v[6:7]
	flat_load_dwordx4 v[170:173], v[8:9]
	flat_load_dwordx4 v[174:177], v[10:11]
	flat_load_dwordx4 v[178:181], v[12:13]
	s_waitcnt vmcnt(0) lgkmcnt(0)
.LBB0_1809:
	v_add_co_u32_e32 v56, vcc, 0xfffff000, v14
	global_load_dwordx4 v[24:27], v[14:15], off offset:-3072
	global_load_dwordx4 v[28:31], v[14:15], off offset:-2048
	global_load_dwordx4 v[32:35], v[14:15], off offset:-1024
	global_load_dwordx4 v[0:3], v[14:15], off
	v_addc_co_u32_e32 v57, vcc, -1, v15, vcc
	global_load_dwordx4 v[36:39], v[56:57], off offset:-3072
	global_load_dwordx4 v[40:43], v[56:57], off offset:-2048
	global_load_dwordx4 v[44:47], v[56:57], off offset:-1024
	global_load_dwordx4 v[48:51], v[14:15], off offset:-4096
	v_mov_b64_e32 v[52:53], v[150:151]
	v_mov_b64_e32 v[54:55], v[152:153]
	s_add_i32 s4, s4, s22
	s_cmpk_gt_i32 s4, 0x1fff
	s_waitcnt vmcnt(0)
	v_mul_f32_e32 v66, v25, v25
	v_mul_f32_e32 v67, v29, v29
	v_mul_f32_e32 v68, v37, v37
	v_mul_f32_e32 v69, v41, v41
	v_mul_f32_e32 v70, v45, v45
	v_fmac_f32_e32 v68, v36, v36
	v_fmac_f32_e32 v69, v40, v40
	v_mov_b32_e32 v60, v33
	v_mov_b32_e32 v61, v1
	v_mul_f32_e32 v71, v49, v49
	v_fmac_f32_e32 v70, v44, v44
	v_fmac_f32_e32 v68, v38, v38
	v_fmac_f32_e32 v69, v42, v42
	v_mov_b32_e32 v58, v32
	v_mov_b32_e32 v59, v0
	v_pk_mul_f32 v[60:61], v[60:61], v[60:61]
	v_fmac_f32_e32 v71, v48, v48
	v_fmac_f32_e32 v70, v46, v46
	v_fmac_f32_e32 v68, v39, v39
	v_fmac_f32_e32 v69, v43, v43
	v_fmac_f32_e32 v66, v24, v24
	v_pk_fma_f32 v[58:59], v[58:59], v[58:59], v[60:61]
	v_fmac_f32_e32 v71, v50, v50
	v_fmac_f32_e32 v70, v47, v47
	v_add_f32_e32 v60, v68, v69
	v_fmac_f32_e32 v67, v28, v28
	v_fmac_f32_e32 v66, v26, v26
	v_fmac_f32_e32 v71, v51, v51
	v_add_f32_e32 v60, v60, v70
	v_mov_b32_e32 v62, v34
	v_mov_b32_e32 v63, v2
	v_fmac_f32_e32 v67, v30, v30
	v_fmac_f32_e32 v66, v27, v27
	v_add_f32_e32 v60, v60, v71
	v_mov_b32_e32 v64, v35
	v_mov_b32_e32 v65, v3
	v_fmac_f32_e32 v67, v31, v31
	v_pk_fma_f32 v[58:59], v[62:63], v[62:63], v[58:59]
	v_add_f32_e32 v60, v60, v66
	v_pk_fma_f32 v[58:59], v[64:65], v[64:65], v[58:59]
	v_add_f32_e32 v60, v60, v67
	v_add_f32_e32 v58, v60, v58
	v_add_f32_e32 v58, v58, v59
	ds_bpermute_b32 v59, v16, v58
	s_waitcnt lgkmcnt(0)
	v_add_f32_e32 v58, v58, v59
	ds_bpermute_b32 v59, v17, v58
	s_waitcnt lgkmcnt(0)
	v_add_f32_e32 v58, v58, v59
	ds_bpermute_b32 v59, v18, v58
	s_waitcnt lgkmcnt(0)
	v_add_f32_e32 v58, v58, v59
	ds_bpermute_b32 v59, v19, v58
	s_waitcnt lgkmcnt(0)
	v_add_f32_e32 v58, v58, v59
	ds_bpermute_b32 v59, v20, v58
	s_waitcnt lgkmcnt(0)
	v_add_f32_e32 v58, v58, v59
	ds_bpermute_b32 v59, v21, v58
	s_waitcnt lgkmcnt(0)
	v_add_f32_e32 v58, v58, v59
	v_fmamk_f32 v58, v58, 0x3a000000, v22
	v_mul_f32_e32 v59, 0x4f800000, v58
	v_cmp_gt_f32_e32 vcc, s5, v58
	s_nop 1
	v_cndmask_b32_e32 v58, v58, v59, vcc
	v_sqrt_f32_e32 v59, v58
	s_nop 0
	v_add_u32_e32 v60, -1, v59
	v_add_u32_e32 v61, 1, v59
	v_fma_f32 v62, -v60, v59, v58
	v_fma_f32 v63, -v61, v59, v58
	v_cmp_ge_f32_e64 s[0:1], 0, v62
	s_nop 1
	v_cndmask_b32_e64 v59, v59, v60, s[0:1]
	v_cmp_lt_f32_e64 s[0:1], 0, v63
	s_nop 1
	v_cndmask_b32_e64 v59, v59, v61, s[0:1]
	v_mul_f32_e32 v60, 0x37800000, v59
	v_cndmask_b32_e32 v59, v59, v60, vcc
	v_cmp_class_f32_e32 vcc, v58, v23
	s_nop 1
	v_cndmask_b32_e32 v58, v59, v58, vcc
	v_div_scale_f32 v59, s[0:1], v58, v58, 1.0
	v_rcp_f32_e32 v60, v59
	v_div_scale_f32 v61, vcc, 1.0, v58, 1.0
	v_fma_f32 v62, -v59, v60, 1.0
	v_fmac_f32_e32 v60, v62, v60
	v_mul_f32_e32 v62, v61, v60
	v_fma_f32 v63, -v59, v62, v61
	v_fmac_f32_e32 v62, v63, v60
	v_fma_f32 v59, -v59, v62, v61
	v_div_fmas_f32 v59, v59, v60, v62
	v_div_fixup_f32 v58, v59, v58, 1.0
	v_pk_mul_f32 v[36:37], v[58:59], v[36:37] op_sel_hi:[0,1]
	v_pk_mul_f32 v[38:39], v[58:59], v[38:39] op_sel_hi:[0,1]
	v_pk_mul_f32 v[38:39], v[54:55], v[38:39]
	v_pk_mul_f32 v[36:37], v[52:53], v[36:37]
	global_store_dwordx4 v[56:57], v[36:39], off offset:-3072
	s_nop 1
	v_mov_b64_e32 v[36:37], v[154:155]
	v_mov_b64_e32 v[38:39], v[156:157]
	v_pk_mul_f32 v[42:43], v[58:59], v[42:43] op_sel_hi:[0,1]
	v_pk_mul_f32 v[40:41], v[58:59], v[40:41] op_sel_hi:[0,1]
	v_pk_mul_f32 v[26:27], v[58:59], v[26:27] op_sel_hi:[0,1]
	v_pk_mul_f32 v[24:25], v[58:59], v[24:25] op_sel_hi:[0,1]
	v_pk_mul_f32 v[30:31], v[58:59], v[30:31] op_sel_hi:[0,1]
	v_pk_mul_f32 v[28:29], v[58:59], v[28:29] op_sel_hi:[0,1]
	v_pk_mul_f32 v[2:3], v[58:59], v[2:3] op_sel_hi:[0,1]
	v_pk_mul_f32 v[0:1], v[58:59], v[0:1] op_sel_hi:[0,1]
	s_waitcnt lgkmcnt(0)
	v_pk_mul_f32 v[36:37], v[36:37], v[40:41]
	v_pk_mul_f32 v[38:39], v[38:39], v[42:43]
	global_store_dwordx4 v[56:57], v[36:39], off offset:-2048
	s_nop 1
	v_mov_b64_e32 v[36:37], v[158:159]
	v_mov_b64_e32 v[38:39], v[160:161]
	v_pk_mul_f32 v[40:41], v[58:59], v[46:47] op_sel_hi:[0,1]
	v_pk_mul_f32 v[42:43], v[58:59], v[44:45] op_sel_hi:[0,1]
	s_waitcnt lgkmcnt(0)
	v_pk_mul_f32 v[36:37], v[36:37], v[42:43]
	v_pk_mul_f32 v[38:39], v[38:39], v[40:41]
	global_store_dwordx4 v[56:57], v[36:39], off offset:-1024
	s_nop 1
	v_mov_b64_e32 v[36:37], v[162:163]
	v_mov_b64_e32 v[38:39], v[164:165]
	v_pk_mul_f32 v[40:41], v[58:59], v[50:51] op_sel_hi:[0,1]
	v_pk_mul_f32 v[42:43], v[58:59], v[48:49] op_sel_hi:[0,1]
	s_waitcnt lgkmcnt(0)
	v_pk_mul_f32 v[36:37], v[36:37], v[42:43]
	v_pk_mul_f32 v[38:39], v[38:39], v[40:41]
	global_store_dwordx4 v[14:15], v[36:39], off offset:-4096
	s_nop 1
	v_mov_b64_e32 v[36:37], v[166:167]
	v_mov_b64_e32 v[38:39], v[168:169]
	s_waitcnt lgkmcnt(0)
	v_pk_mul_f32 v[24:25], v[36:37], v[24:25]
	v_pk_mul_f32 v[26:27], v[38:39], v[26:27]
	global_store_dwordx4 v[14:15], v[24:27], off offset:-3072
	s_nop 1
	v_mov_b64_e32 v[24:25], v[170:171]
	v_mov_b64_e32 v[26:27], v[172:173]
	s_waitcnt lgkmcnt(0)
	v_pk_mul_f32 v[24:25], v[24:25], v[28:29]
	v_pk_mul_f32 v[26:27], v[26:27], v[30:31]
	global_store_dwordx4 v[14:15], v[24:27], off offset:-2048
	s_nop 1
	v_mov_b64_e32 v[24:25], v[174:175]
	v_mov_b64_e32 v[26:27], v[176:177]
	v_pk_mul_f32 v[28:29], v[58:59], v[34:35] op_sel_hi:[0,1]
	v_pk_mul_f32 v[30:31], v[58:59], v[32:33] op_sel_hi:[0,1]
	s_waitcnt lgkmcnt(0)
	v_pk_mul_f32 v[24:25], v[24:25], v[30:31]
	v_pk_mul_f32 v[26:27], v[26:27], v[28:29]
	global_store_dwordx4 v[14:15], v[24:27], off offset:-1024
	s_nop 1
	v_mov_b64_e32 v[24:25], v[178:179]
	v_mov_b64_e32 v[26:27], v[180:181]
	s_waitcnt lgkmcnt(0)
	v_pk_mul_f32 v[0:1], v[24:25], v[0:1]
	v_pk_mul_f32 v[2:3], v[26:27], v[2:3]
	global_store_dwordx4 v[14:15], v[0:3], off
	v_lshl_add_u64 v[14:15], v[14:15], 0, s[2:3]
	s_cbranch_scc0 .LBB0_1809
